# experiment: s_sleep 7 for waves 4-7 after each step barrier in retention loop (stagger)
# baseline (speedup 1.0000x reference)
.LBB0_1370:
	s_add_i32 s1, s57, -1
	s_waitcnt vmcnt(7)
	ds_write_b128 v175, v[72:75]
	ds_write_b128 v175, v[68:71] offset:8704
	ds_write_b128 v175, v[64:67] offset:17408
	v_cndmask_b32_e32 v65, v180, v173, vcc
	v_xor_b32_e32 v66, 0xffffffef, v173
	v_xor_b32_e32 v70, 0xffffffcf, v173
	s_min_u32 s18, s1, s0
	v_add_u32_e32 v69, 48, v173
	v_xor_b32_e32 v67, 0xffffffdf, v173
	v_add_u32_e32 v71, s55, v66
	v_add_u32_e32 v66, s56, v65
	v_add_u32_e32 v70, s55, v70
	v_lshl_add_u32 v73, s18, 5, v174
	v_add_u32_e32 v64, 16, v173
	v_add_u32_e32 v68, 32, v173
	v_add_u32_e32 v65, s55, v67
	v_ashrrev_i32_e32 v67, 31, v66
	v_cndmask_b32_e32 v69, v70, v69, vcc
	v_xad_u32 v70, v73, -1, s55
	v_cndmask_b32_e32 v71, v71, v64, vcc
	v_cndmask_b32_e32 v68, v65, v68, vcc
	v_lshlrev_b64 v[64:65], 11, v[66:67]
	v_cndmask_b32_e32 v67, v70, v73, vcc
	s_min_u32 s42, s57, s0
	v_lshl_add_u64 v[242:243], v[170:171], 0, v[64:65]
	v_add_u32_e32 v64, s56, v67
	v_lshl_add_u32 v72, s42, 5, v174
	v_ashrrev_i32_e32 v65, 31, v64
	v_cvt_pk_bf16_f32 v60, v44, v45
	v_cvt_pk_bf16_f32 v61, v46, v47
	v_cvt_pk_bf16_f32 v62, v40, v41
	v_cvt_pk_bf16_f32 v63, v42, v43
	v_xad_u32 v74, v72, -1, s55
	v_lshlrev_b64 v[64:65], 13, v[64:65]
	v_cndmask_b32_e32 v66, v74, v72, vcc
	v_or_b32_e32 v64, v64, v181
	v_add_u32_e32 v238, s56, v68
	v_add_u32_e32 v240, s56, v69
	v_add_u32_e32 v244, s56, v66
	v_lshl_add_u64 v[66:67], s[36:37], 0, v[64:65]
	v_lshl_add_u64 v[68:69], s[38:39], 0, v[64:65]
	v_lshl_add_u64 v[64:65], s[40:41], 0, v[64:65]
	v_add_u32_e32 v0, 0x1000, v178
	v_add_u32_e32 v1, 0x2000, v179
	v_add_u32_e32 v182, 0x3000, v179
	v_add_u32_e32 v236, s56, v71
	global_load_dwordx4 v[72:75], v[66:67], off
	s_nop 0
	global_load_dwordx4 v[68:71], v[68:69], off
	s_nop 0
	global_load_dwordx4 v[64:67], v[64:65], off
	s_waitcnt lgkmcnt(0)
	s_barrier
	s_cselect_b32 s99, 1, 0
	s_cmp_eq_u32 s98, 0
	s_cbranch_scc1 .Lstg_skip1
	s_sleep 7
.Lstg_skip1:
	s_cmp_lg_u32 s99, 0
	ds_read_b64 v[188:189], v178
	ds_read_b64 v[190:191], v178 offset:32
	ds_read_b64 v[192:193], v0 offset:256
	ds_read_b64 v[194:195], v0 offset:288
	ds_read_b64 v[196:197], v0 offset:320
	ds_read_b64 v[198:199], v0 offset:352
	ds_read_b64 v[200:201], v1 offset:512
	ds_read_b64 v[202:203], v1 offset:544
	ds_read_b64 v[204:205], v182 offset:768
	ds_read_b64 v[206:207], v182 offset:800
	ds_read_b64_tr_b16 v[210:211], v176 offset:13056
	ds_read_b64_tr_b16 v[212:213], v177 offset:17408
	ds_read_b64_tr_b16 v[214:215], v177 offset:21760
	ds_read_b64_tr_b16 v[208:209], v176 offset:8704
	ds_read_b64_tr_b16 v[216:217], v176 offset:8736
	ds_read_b64_tr_b16 v[220:221], v176 offset:8768
	ds_read_b64_tr_b16 v[222:223], v176 offset:13120
	ds_read_b64_tr_b16 v[218:219], v176 offset:13088
	ds_read_b64_tr_b16 v[230:231], v176 offset:8928
	s_waitcnt lgkmcnt(7)
	v_lshlrev_b32_e32 v232, 16, v212
	v_and_b32_e32 v233, 0xffff0000, v212
	v_lshlrev_b32_e32 v234, 16, v213
	v_and_b32_e32 v235, 0xffff0000, v213
	s_waitcnt lgkmcnt(6)
	v_lshlrev_b32_e32 v246, 16, v214
	v_and_b32_e32 v247, 0xffff0000, v214
	v_lshlrev_b32_e32 v248, 16, v215
	v_and_b32_e32 v249, 0xffff0000, v215
	v_mov_b32_e32 v159, v158
	v_mfma_f32_16x16x32_bf16 v[226:229], v[60:63], v[192:195], 0
	v_mul_f32_e64 v232, v150, v232
	v_mul_f32_e64 v233, v151, v233
	v_pk_mul_f32 v[234:235], v[152:153], v[234:235]
	v_pk_mul_f32 v[44:45], v[164:165], v[44:45]
	v_mfma_f32_16x16x32_bf16 v[60:63], v[60:63], v[188:191], 0
	v_mul_f32_e64 v46, v158, v46
	v_mul_f32_e64 v47, v159, v47
	v_pk_mul_f32 v[40:41], v[164:165], v[40:41]
	v_pk_mul_f32 v[42:43], v[158:159], v[42:43]
	v_mfma_f32_16x16x32_bf16 v[188:191], v[200:203], v[188:191], 0
	v_cvt_pk_bf16_f32 v52, v36, v37
	v_cvt_pk_bf16_f32 v53, v38, v39
	v_cvt_pk_bf16_f32 v54, v32, v33
	v_mfma_f32_16x16x32_bf16 v[200:203], v[200:203], v[192:195], 0
	v_cvt_pk_bf16_f32 v55, v34, v35
	v_cvt_pk_bf16_f32 v56, v28, v29
	v_cvt_pk_bf16_f32 v57, v30, v31
	v_mfma_f32_16x16x32_bf16 v[192:195], v[204:207], v[192:195], 0
	v_mul_f32_e64 v206, v154, v246
	v_mul_f32_e64 v207, v155, v247
	v_pk_mul_f32 v[246:247], v[156:157], v[248:249]
	v_cvt_pk_bf16_f32 v204, v232, v233
	v_cvt_pk_bf16_f32 v205, v234, v235
	v_cvt_pk_bf16_f32 v206, v206, v207
	v_cvt_pk_bf16_f32 v207, v246, v247
	v_pk_mul_f32 v[36:37], v[164:165], v[36:37]
	v_pk_mul_f32 v[32:33], v[164:165], v[32:33]
	s_waitcnt lgkmcnt(5)
	v_mfma_f32_16x16x32_bf16 v[44:47], v[208:211], v[204:207], v[44:47]
	ds_read_b64_tr_b16 v[210:211], v176 offset:13152
	ds_read_b64_tr_b16 v[208:209], v176 offset:8800
	ds_read_b64_tr_b16 v[232:233], v176 offset:8832
	v_pk_mul_f32 v[28:29], v[164:165], v[28:29]
	v_pk_mul_f32 v[38:39], v[158:159], v[38:39]
	s_waitcnt lgkmcnt(4)
	v_mfma_f32_16x16x32_bf16 v[40:43], v[216:219], v[204:207], v[40:43]
	ds_read_b64_tr_b16 v[216:217], v176 offset:8864
	ds_read_b64_tr_b16 v[234:235], v176 offset:13184
	ds_read_b64_tr_b16 v[218:219], v176 offset:13216
	v_pk_mul_f32 v[34:35], v[158:159], v[34:35]
	v_pk_mul_f32 v[30:31], v[158:159], v[30:31]
	v_mfma_f32_16x16x32_bf16 v[36:39], v[220:223], v[204:207], v[36:39]
	v_ashrrev_i32_e32 v245, 31, v244
	v_ashrrev_i32_e32 v237, 31, v236
	v_cvt_pk_bf16_f32 v58, v24, v25
	s_waitcnt lgkmcnt(4)
	v_mfma_f32_16x16x32_bf16 v[32:35], v[208:211], v[204:207], v[32:35]
	ds_read_b64_tr_b16 v[208:209], v176 offset:8896
	ds_read_b64_tr_b16 v[210:211], v176 offset:13248
	v_cvt_pk_bf16_f32 v59, v26, v27
	s_waitcnt lgkmcnt(3)
	v_mfma_f32_16x16x32_bf16 v[220:223], v[232:235], v[204:207], v[28:31]
	ds_read_b64_tr_b16 v[232:233], v176 offset:13280
	v_cvt_pk_bf16_f32 v48, v20, v21
	v_cvt_pk_bf16_f32 v49, v22, v23
	v_lshlrev_b64 v[28:29], 13, v[244:245]
	v_cvt_pk_bf16_f32 v50, v16, v17
	v_cvt_pk_bf16_f32 v51, v18, v19
	v_pk_mul_f32 v[24:25], v[164:165], v[24:25]
	v_pk_mul_f32 v[20:21], v[164:165], v[20:21]
	v_pk_mul_f32 v[16:17], v[164:165], v[16:17]
	v_pk_mul_f32 v[26:27], v[158:159], v[26:27]
	v_pk_mul_f32 v[22:23], v[158:159], v[22:23]
	v_pk_mul_f32 v[18:19], v[158:159], v[18:19]
	v_ashrrev_i32_e32 v239, 31, v238
	v_ashrrev_i32_e32 v241, 31, v240
	v_lshlrev_b64 v[236:237], 11, v[236:237]
	v_or_b32_e32 v28, v28, v181
	v_lshlrev_b64 v[246:247], 11, v[238:239]
	v_lshlrev_b64 v[248:249], 11, v[240:241]
	s_waitcnt lgkmcnt(3)
	v_mfma_f32_16x16x32_bf16 v[216:219], v[216:219], v[204:207], v[24:27]
	v_lshl_add_u64 v[234:235], v[170:171], 0, v[236:237]
	v_lshl_add_u64 v[236:237], s[36:37], 0, v[28:29]
	v_lshl_add_u64 v[238:239], s[38:39], 0, v[28:29]
	s_waitcnt lgkmcnt(1)
	v_mfma_f32_16x16x32_bf16 v[208:211], v[208:211], v[204:207], v[20:23]
	ds_read_b64 v[24:25], v1 offset:576
	ds_read_b64 v[26:27], v1 offset:608
	v_lshl_add_u64 v[240:241], s[40:41], 0, v[28:29]
	ds_read_b64 v[28:29], v182 offset:832
	ds_read_b64 v[30:31], v182 offset:864
	s_waitcnt lgkmcnt(4)
	v_mfma_f32_16x16x32_bf16 v[204:207], v[230:233], v[204:207], v[16:19]
	v_mov_b32_e32 v3, v2
	v_add_u32_e32 v183, 0x6000, v178
	v_add_u32_e32 v184, 0x7000, v178
	ds_read_b64 v[16:17], v178 offset:64
	ds_read_b64 v[18:19], v178 offset:96
	v_mfma_f32_16x16x32_bf16 v[226:229], v[52:55], v[196:199], v[226:229]
	v_add_u32_e32 v185, 0x8800, v179
	v_add_u32_e32 v186, 0x9800, v179
	s_add_i32 s57, s57, 2
	s_waitcnt lgkmcnt(0)
	v_mfma_f32_16x16x32_bf16 v[20:23], v[52:55], v[16:19], v[60:63]
	ds_read_b64 v[52:53], v0 offset:384
	ds_read_b64 v[54:55], v0 offset:416
	s_nop 1
	ds_read_b64 v[60:61], v178 offset:128
	ds_read_b64 v[62:63], v178 offset:160
	v_add_u32_e32 v173, 64, v173
	v_subrev_u32_e32 v180, 64, v180
	v_mfma_f32_16x16x32_bf16 v[16:19], v[24:27], v[16:19], v[188:191]
	s_cmp_ge_u32 s1, s58
	v_mfma_f32_16x16x32_bf16 v[24:27], v[24:27], v[196:199], v[200:203]
	v_mfma_f32_16x16x32_bf16 v[28:31], v[28:31], v[196:199], v[192:195]
	s_nop 2
	ds_read_b64 v[192:193], v1 offset:640
	ds_read_b64 v[194:195], v1 offset:672
	ds_read_b64 v[196:197], v178 offset:192
	ds_read_b64 v[198:199], v178 offset:224
	ds_read_b64 v[200:201], v0 offset:448
	ds_read_b64 v[202:203], v0 offset:480
	s_waitcnt lgkmcnt(8)
	v_mfma_f32_16x16x32_bf16 v[188:191], v[56:59], v[52:55], v[226:229]
	s_waitcnt lgkmcnt(6)
	v_mfma_f32_16x16x32_bf16 v[20:23], v[56:59], v[60:63], v[20:23]
	ds_read_b64 v[56:57], v182 offset:896
	ds_read_b64 v[58:59], v182 offset:928
	ds_read_b64 v[226:227], v1 offset:704
	ds_read_b64 v[228:229], v1 offset:736
	ds_read_b64 v[230:231], v182 offset:960
	ds_read_b64 v[232:233], v182 offset:992
	s_waitcnt vmcnt(5)
	ds_write_b128 v175, v[12:15] offset:26112
	ds_write_b128 v175, v[8:11] offset:34816
	ds_write_b128 v175, v[4:7] offset:43520
	s_waitcnt lgkmcnt(13)
	v_mfma_f32_16x16x32_bf16 v[16:19], v[192:195], v[60:63], v[16:19]
	v_mfma_f32_16x16x32_bf16 v[4:7], v[192:195], v[52:55], v[24:27]
	s_waitcnt lgkmcnt(7)
	v_mfma_f32_16x16x32_bf16 v[8:11], v[56:59], v[52:55], v[28:31]
	s_nop 0
	v_cvt_pk_bf16_f32 v24, v44, v45
	v_cvt_pk_bf16_f32 v25, v46, v47
	v_cvt_pk_bf16_f32 v26, v40, v41
	s_waitcnt lgkmcnt(5)
	v_mfma_f32_16x16x32_bf16 v[16:19], v[226:229], v[196:199], v[16:19]
	v_mul_f32_e64 v28, v164, v44
	v_mul_f32_e64 v29, v165, v45
	v_cvt_pk_bf16_f32 v27, v42, v43
	v_pk_mul_f32 v[30:31], v[158:159], v[46:47]
	v_mfma_f32_16x16x32_bf16 v[4:7], v[226:229], v[200:203], v[4:7]
	v_cvt_pk_bf16_f32 v52, v36, v37
	s_nop 1
	v_pk_mul_f32 v[18:19], v[146:147], v[18:19]
	v_pk_mul_f32 v[0:1], v[142:143], v[16:17]
	s_waitcnt lgkmcnt(3)
	v_mfma_f32_16x16x32_bf16 v[8:11], v[230:233], v[200:203], v[8:11]
	v_cvt_pk_bf16_f32 v0, v0, v1
	v_pk_mul_f32 v[6:7], v[148:149], v[6:7]
	v_pk_mul_f32 v[4:5], v[144:145], v[4:5]
	v_cvt_pk_bf16_f32 v1, v18, v19
	v_cvt_pk_bf16_f32 v4, v4, v5
	s_nop 2
	v_pk_mul_f32 v[16:17], v[146:147], v[10:11]
	v_pk_mul_f32 v[44:45], v[142:143], v[8:9]
	v_cvt_pk_bf16_f32 v5, v6, v7
	v_cvt_pk_bf16_f32 v6, v44, v45
	v_cvt_pk_bf16_f32 v7, v16, v17
	v_mfma_f32_16x16x32_bf16 v[12:15], v[48:51], v[200:203], v[188:191]
	v_cvt_pk_bf16_f32 v53, v38, v39
	v_pk_mul_f32 v[38:39], v[158:159], v[38:39]
	v_pk_mul_f32 v[36:37], v[164:165], v[36:37]
	v_mfma_f32_16x16x32_bf16 v[20:23], v[48:51], v[196:199], v[20:23]
	v_cvt_pk_bf16_f32 v54, v32, v33
	v_cvt_pk_bf16_f32 v55, v34, v35
	v_pk_mul_f32 v[42:43], v[158:159], v[42:43]
	v_mfma_f32_16x16x32_bf16 v[8:11], v[212:215], v[0:3], 0
	v_mul_f32_e64 v40, v164, v40
	v_mul_f32_e64 v41, v165, v41
	v_pk_mul_f32 v[34:35], v[158:159], v[34:35]
	v_pk_mul_f32 v[32:33], v[164:165], v[32:33]
	v_mfma_f32_16x16x32_bf16 v[4:7], v[212:215], v[4:7], 0
	v_mul_f32_e64 v50, v158, v222
	v_mul_f32_e64 v51, v159, v223
	s_nop 0
	v_pk_fma_f32 v[8:9], v[162:163], v[20:21], v[8:9]
	v_pk_mul_f32 v[48:49], v[164:165], v[220:221]
	v_cvt_pk_bf16_f32 v8, v8, v9
	v_cvt_pk_bf16_f32 v56, v220, v221
	s_nop 0
	v_pk_fma_f32 v[0:1], v[166:167], v[14:15], v[6:7]
	v_pk_fma_f32 v[6:7], v[168:169], v[22:23], v[10:11]
	v_pk_fma_f32 v[4:5], v[160:161], v[12:13], v[4:5]
	v_cvt_pk_bf16_f32 v9, v6, v7
	v_cvt_pk_bf16_f32 v4, v4, v5
	v_cvt_pk_bf16_f32 v5, v0, v1
	global_store_dwordx2 v[242:243], v[8:9], off
	global_store_dwordx2 v[234:235], v[4:5], off
	global_load_dwordx4 v[12:15], v[236:237], off
	s_nop 0
	global_load_dwordx4 v[8:11], v[238:239], off
	global_load_dwordx4 v[4:7], v[240:241], off
	s_waitcnt lgkmcnt(0)
	s_barrier
	s_cselect_b32 s99, 1, 0
	s_cmp_eq_u32 s98, 0
	s_cbranch_scc1 .Lstg_skip2
	s_sleep 7
